# grid barrier: the per-CU L1 invalidate is issued by wave 1 at barrier entry, in parallel with wave 0's arrive / write-back / poll chain
# speedup vs baseline: 1.0349x; 1.0027x over previous
.LBB0_563:
	s_waitcnt vmcnt(0)
	s_waitcnt vmcnt(0) lgkmcnt(0)
	s_barrier
	v_readfirstlane_b32 s2, v202
	s_lshr_b32 s2, s2, 6
	s_cmp_eq_u32 s2, 1
	s_cbranch_scc0 .Lxb_noinv
	buffer_inv sc1
	s_waitcnt vmcnt(0)
.Lxb_noinv:
	s_mov_b64 s[0:1], exec
	v_readlane_b32 s2, v252, 0
	v_readlane_b32 s3, v252, 1
	s_and_b64 s[2:3], s[0:1], s[2:3]
	s_mov_b64 exec, s[2:3]
	s_cbranch_execnz .LBB0_564
	s_getpc_b64 s[98:99]

.LBB0_579:
	v_readlane_b32 s12, v253, 46
	v_readlane_b32 s13, v253, 47
	v_readlane_b32 s14, v253, 50
	v_readlane_b32 s15, v253, 51
	v_mov_b32_e32 v1, 0
	v_mov_b32_e32 v6, 1
	s_waitcnt lgkmcnt(0)
	s_nop 4
	global_atomic_add v6, v1, v6, s[12:13] sc0
	v_cvt_f32_u32_e32 v5, v3
	v_sub_u32_e32 v4, 0, v3
	v_rcp_iflag_f32_e32 v5, v5
	s_nop 1
	v_mul_f32_e32 v5, 0x4f7ffffe, v5
	v_cvt_u32_f32_e32 v5, v5
	v_mul_lo_u32 v0, v4, v5
	v_mul_hi_u32 v0, v5, v0
	v_add_u32_e32 v0, v5, v0
	s_waitcnt vmcnt(0)
	v_mul_hi_u32 v0, v6, v0
	v_mul_lo_u32 v4, v0, v3
	v_sub_u32_e32 v4, v6, v4
	v_add_u32_e32 v5, 1, v0
	v_cmp_ge_u32_e32 vcc, v4, v3
	s_nop 1
	v_cndmask_b32_e32 v0, v0, v5, vcc
	v_sub_u32_e32 v5, v4, v3
	v_cndmask_b32_e32 v4, v4, v5, vcc
	v_add_u32_e32 v5, 1, v0
	v_cmp_ge_u32_e32 vcc, v4, v3
	s_nop 1
	v_cndmask_b32_e32 v0, v0, v5, vcc
	v_add_u32_e32 v0, 1, v0
	v_mul_lo_u32 v4, v0, v3
	v_mul_lo_u32 v5, v0, v2
	v_add_u32_e32 v6, 1, v6
	v_cmp_ne_u32_e32 vcc, v6, v4
	s_mov_b32 s16, 0
	s_cbranch_vccnz .Lxb_wait
	buffer_wbl2 sc1
	s_waitcnt vmcnt(0)
	v_mov_b32_e32 v4, 1
	global_atomic_add v1, v4, s[14:15]
	s_branch .Lxb_poll
.Lxb_wait:
.Lxb_poll:
	global_load_dword v4, v1, s[14:15] sc1
	s_waitcnt vmcnt(0)
	v_cmp_lt_u32_e32 vcc, v4, v5
	s_cbranch_vccz .Lxb_done
	s_add_i32 s16, s16, 1
	s_cmp_lt_u32 s16, 0x40000
	s_cbranch_scc0 .Lxb_done
	s_sleep 1
	s_branch .Lxb_poll
